# banded attention item epilogues: O stores widened with v_permlane32_swap pairs (dwordx2 -> dwordx4), on top of v45
# baseline (speedup 1.0000x reference)
.LBB0_900:
	ds_bpermute_b32 v0, v210, v214
	s_lshl_b32 s4, s49, 12
	s_or_b32 s6, s4, s50
	s_lshl_b32 s16, s48, 7
	s_add_i32 s47, s47, s58
	s_waitcnt lgkmcnt(0)
	v_add_f32_e32 v1, v214, v0
	v_div_scale_f32 v2, s[4:5], v1, v1, 1.0
	v_rcp_f32_e32 v3, v2
	v_div_scale_f32 v4, vcc, 1.0, v1, 1.0
	v_or_b32_e32 v0, s6, v178
	v_fma_f32 v5, -v2, v3, 1.0
	v_fmac_f32_e32 v3, v5, v3
	v_mul_f32_e32 v5, v4, v3
	v_fma_f32 v6, -v2, v5, v4
	v_fmac_f32_e32 v5, v6, v3
	v_fma_f32 v2, -v2, v5, v4
	v_div_fmas_f32 v2, v2, v3, v5
	v_div_fixup_f32 v2, v2, v1, 1.0
	v_ashrrev_i32_e32 v1, 31, v0
	v_lshlrev_b64 v[0:1], 11, v[0:1]
	v_lshl_add_u64 v[0:1], s[0:1], 0, v[0:1]
	v_lshl_add_u64 v[0:1], v[0:1], 0, s[16:17]
	v_lshl_add_u64 v[0:1], v[202:203], 2, v[0:1]
	v_pk_mul_f32 v[50:51], v[50:51], v[2:3] op_sel_hi:[1,0]
	v_pk_mul_f32 v[52:53], v[52:53], v[2:3] op_sel_hi:[1,0]
	v_pk_mul_f32 v[54:55], v[54:55], v[2:3] op_sel_hi:[1,0]
	v_pk_mul_f32 v[56:57], v[56:57], v[2:3] op_sel_hi:[1,0]
	v_cvt_pk_bf16_f32 v66, v50, v51
	v_cvt_pk_bf16_f32 v67, v52, v53
	v_cvt_pk_bf16_f32 v68, v54, v55
	v_cvt_pk_bf16_f32 v69, v56, v57
	s_nop 1
	v_permlane32_swap_b32 v66, v68
	v_permlane32_swap_b32 v67, v69
	global_store_dwordx4 v[0:1], v[66:69], off
	v_pk_mul_f32 v[58:59], v[58:59], v[2:3] op_sel_hi:[1,0]
	v_pk_mul_f32 v[60:61], v[60:61], v[2:3] op_sel_hi:[1,0]
	v_pk_mul_f32 v[62:63], v[62:63], v[2:3] op_sel_hi:[1,0]
	v_pk_mul_f32 v[64:65], v[64:65], v[2:3] op_sel_hi:[1,0]
	v_cvt_pk_bf16_f32 v70, v58, v59
	v_cvt_pk_bf16_f32 v71, v60, v61
	v_cvt_pk_bf16_f32 v72, v62, v63
	v_cvt_pk_bf16_f32 v73, v64, v65
	s_nop 1
	v_permlane32_swap_b32 v70, v72
	v_permlane32_swap_b32 v71, v73
	global_store_dwordx4 v[0:1], v[70:73], off offset:32
	v_pk_mul_f32 v[34:35], v[34:35], v[2:3] op_sel_hi:[1,0]
	v_pk_mul_f32 v[36:37], v[36:37], v[2:3] op_sel_hi:[1,0]
	v_pk_mul_f32 v[38:39], v[38:39], v[2:3] op_sel_hi:[1,0]
	v_pk_mul_f32 v[40:41], v[40:41], v[2:3] op_sel_hi:[1,0]
	v_cvt_pk_bf16_f32 v74, v34, v35
	v_cvt_pk_bf16_f32 v75, v36, v37
	v_cvt_pk_bf16_f32 v76, v38, v39
	v_cvt_pk_bf16_f32 v77, v40, v41
	s_nop 1
	v_permlane32_swap_b32 v74, v76
	v_permlane32_swap_b32 v75, v77
	global_store_dwordx4 v[0:1], v[74:77], off offset:64
	v_readlane_b32 s4, v254, 43
	v_pk_mul_f32 v[42:43], v[42:43], v[2:3] op_sel_hi:[1,0]
	v_pk_mul_f32 v[44:45], v[44:45], v[2:3] op_sel_hi:[1,0]
	v_pk_mul_f32 v[46:47], v[46:47], v[2:3] op_sel_hi:[1,0]
	v_pk_mul_f32 v[48:49], v[48:49], v[2:3] op_sel_hi:[1,0]
	v_cvt_pk_bf16_f32 v78, v42, v43
	v_cvt_pk_bf16_f32 v79, v44, v45
	v_cvt_pk_bf16_f32 v80, v46, v47
	v_cvt_pk_bf16_f32 v81, v48, v49
	s_nop 1
	v_permlane32_swap_b32 v78, v80
	v_permlane32_swap_b32 v79, v81
	global_store_dwordx4 v[0:1], v[78:81], off offset:96
	s_add_i32 s46, s46, s4
	s_cmpk_gt_i32 s47, 0x3fff
	s_cbranch_scc1 .LBB0_911

.LBB0_927:
	ds_bpermute_b32 v0, v208, v211
	s_add_i32 s69, s69, -1
	s_waitcnt lgkmcnt(0)
	v_add_f32_e32 v0, v211, v0
	v_div_scale_f32 v1, s[4:5], v0, v0, 1.0
	v_rcp_f32_e32 v2, v1
	s_ashr_i32 s4, s67, s43
	s_and_b32 s5, s67, s69
	s_lshl_b32 s4, s4, 12
	v_fma_f32 v3, -v1, v2, 1.0
	v_fmac_f32_e32 v2, v3, v2
	v_div_scale_f32 v3, vcc, 1.0, v0, 1.0
	v_mul_f32_e32 v4, v3, v2
	v_fma_f32 v5, -v1, v4, v3
	v_fmac_f32_e32 v4, v5, v2
	v_fma_f32 v1, -v1, v4, v3
	v_div_fmas_f32 v1, v1, v2, v4
	v_div_fixup_f32 v2, v1, v0, 1.0
	s_add_i32 s4, s4, s5
	v_lshlrev_b32_e32 v1, s43, v32
	v_add_u32_e32 v1, s4, v1
	v_mov_b64_e32 v[4:5], s[0:1]
	s_movk_i32 s4, 0x900
	v_mad_i64_i32 v[4:5], s[4:5], v1, s4, v[4:5]
	s_lshl_b32 s4, s42, 6
	s_ashr_i32 s5, s4, 31
	v_lshl_add_u64 v[4:5], s[4:5], 1, v[4:5]
	v_lshl_add_u64 v[4:5], v[182:183], 2, v[4:5]
	v_pk_mul_f32 v[50:51], v[50:51], v[2:3] op_sel_hi:[1,0]
	v_pk_mul_f32 v[52:53], v[52:53], v[2:3] op_sel_hi:[1,0]
	v_pk_mul_f32 v[54:55], v[54:55], v[2:3] op_sel_hi:[1,0]
	v_pk_mul_f32 v[56:57], v[56:57], v[2:3] op_sel_hi:[1,0]
	v_cvt_pk_bf16_f32 v66, v50, v51
	v_cvt_pk_bf16_f32 v67, v52, v53
	v_cvt_pk_bf16_f32 v68, v54, v55
	v_cvt_pk_bf16_f32 v69, v56, v57
	s_nop 1
	v_permlane32_swap_b32 v66, v68
	v_permlane32_swap_b32 v67, v69
	global_store_dwordx4 v[4:5], v[66:69], off
	v_pk_mul_f32 v[58:59], v[58:59], v[2:3] op_sel_hi:[1,0]
	v_pk_mul_f32 v[60:61], v[60:61], v[2:3] op_sel_hi:[1,0]
	v_pk_mul_f32 v[62:63], v[62:63], v[2:3] op_sel_hi:[1,0]
	v_pk_mul_f32 v[64:65], v[64:65], v[2:3] op_sel_hi:[1,0]
	v_cvt_pk_bf16_f32 v70, v58, v59
	v_cvt_pk_bf16_f32 v71, v60, v61
	v_cvt_pk_bf16_f32 v72, v62, v63
	v_cvt_pk_bf16_f32 v73, v64, v65
	s_nop 1
	v_permlane32_swap_b32 v70, v72
	v_permlane32_swap_b32 v71, v73
	global_store_dwordx4 v[4:5], v[70:73], off offset:32
	v_pk_mul_f32 v[34:35], v[34:35], v[2:3] op_sel_hi:[1,0]
	v_pk_mul_f32 v[36:37], v[36:37], v[2:3] op_sel_hi:[1,0]
	v_pk_mul_f32 v[38:39], v[38:39], v[2:3] op_sel_hi:[1,0]
	v_pk_mul_f32 v[40:41], v[40:41], v[2:3] op_sel_hi:[1,0]
	v_cvt_pk_bf16_f32 v74, v34, v35
	v_cvt_pk_bf16_f32 v75, v36, v37
	v_cvt_pk_bf16_f32 v76, v38, v39
	v_cvt_pk_bf16_f32 v77, v40, v41
	s_nop 1
	v_permlane32_swap_b32 v74, v76
	v_permlane32_swap_b32 v75, v77
	global_store_dwordx4 v[4:5], v[74:77], off offset:64
	v_pk_mul_f32 v[42:43], v[42:43], v[2:3] op_sel_hi:[1,0]
	v_pk_mul_f32 v[44:45], v[44:45], v[2:3] op_sel_hi:[1,0]
	v_pk_mul_f32 v[46:47], v[46:47], v[2:3] op_sel_hi:[1,0]
	v_pk_mul_f32 v[48:49], v[48:49], v[2:3] op_sel_hi:[1,0]
	v_cvt_pk_bf16_f32 v78, v42, v43
	v_cvt_pk_bf16_f32 v79, v44, v45
	v_cvt_pk_bf16_f32 v80, v46, v47
	v_cvt_pk_bf16_f32 v81, v48, v49
	s_nop 1
	v_permlane32_swap_b32 v78, v80
	v_permlane32_swap_b32 v79, v81
	global_store_dwordx4 v[4:5], v[78:81], off offset:96
	s_and_saveexec_b64 s[44:45], s[38:39]
	s_cbranch_execz .LBB0_915
	v_log_f32_e32 v0, v0
	v_mov_b64_e32 v[2:3], s[40:41]
	s_movk_i32 s4, 0x48
	s_ashr_i32 s43, s42, 31
	v_add_f32_e32 v4, v210, v0
	v_mad_i64_i32 v[0:1], s[4:5], v1, s4, v[2:3]
	v_lshl_add_u64 v[0:1], s[42:43], 2, v[0:1]
	global_store_dword v[0:1], v4, off
	s_branch .LBB0_915
